# sample cross-attention K/V cache loads with agent-scope streaming policy (sc1 nt instead of nt)
# baseline (speedup 1.0000x reference)
.LBB11_2193:
	s_lshl_b32 s1, s0, 4
	s_or_b32 s60, s1, s76
	s_lshl_b64 s[48:49], s[60:61], 12
	s_waitcnt lgkmcnt(0)
	v_lshl_add_u64 v[2:3], v[62:63], 0, s[48:49]
	s_or_b32 s48, s60, 1
	s_mov_b32 s49, s61
	s_lshl_b64 s[48:49], s[48:49], 12
	v_lshl_add_u64 v[4:5], v[62:63], 0, s[48:49]
	global_load_dwordx4 v[68:71], v[2:3], off sc1 nt
	global_load_dwordx4 v[58:61], v[4:5], off sc1 nt
	s_or_b32 s48, s60, 2
	s_mov_b32 s49, s61
	s_lshl_b64 s[48:49], s[48:49], 12
	v_lshl_add_u64 v[2:3], v[62:63], 0, s[48:49]
	s_or_b32 s48, s60, 3
	s_mov_b32 s49, s61
	s_lshl_b64 s[48:49], s[48:49], 12
	v_lshl_add_u64 v[4:5], v[62:63], 0, s[48:49]
	s_or_b32 s48, s60, 4
	s_mov_b32 s49, s61
	s_lshl_b64 s[48:49], s[48:49], 12
	global_load_dwordx4 v[54:57], v[2:3], off sc1 nt
	global_load_dwordx4 v[50:53], v[4:5], off sc1 nt
	v_lshl_add_u64 v[2:3], v[62:63], 0, s[48:49]
	s_or_b32 s48, s60, 5
	s_mov_b32 s49, s61
	s_lshl_b64 s[48:49], s[48:49], 12
	v_lshl_add_u64 v[4:5], v[62:63], 0, s[48:49]
	s_or_b32 s48, s60, 6
	s_mov_b32 s49, s61
	s_lshl_b64 s[48:49], s[48:49], 12
	global_load_dwordx4 v[46:49], v[2:3], off sc1 nt
	global_load_dwordx4 v[42:45], v[4:5], off sc1 nt
	v_lshl_add_u64 v[2:3], v[62:63], 0, s[48:49]
	s_or_b32 s48, s60, 7
	s_mov_b32 s49, s61
	s_lshl_b64 s[48:49], s[48:49], 12
	v_lshl_add_u64 v[4:5], v[62:63], 0, s[48:49]
	s_or_b32 s48, s60, 8
	s_mov_b32 s49, s61
	s_lshl_b64 s[48:49], s[48:49], 12
	global_load_dwordx4 v[38:41], v[2:3], off sc1 nt
	global_load_dwordx4 v[34:37], v[4:5], off sc1 nt
	v_lshl_add_u64 v[2:3], v[62:63], 0, s[48:49]
	s_or_b32 s48, s60, 9
	s_mov_b32 s49, s61
	s_lshl_b64 s[48:49], s[48:49], 12
	v_lshl_add_u64 v[4:5], v[62:63], 0, s[48:49]
	s_or_b32 s48, s60, 10
	s_mov_b32 s49, s61
	s_lshl_b64 s[48:49], s[48:49], 12
	global_load_dwordx4 v[30:33], v[2:3], off sc1 nt
	global_load_dwordx4 v[26:29], v[4:5], off sc1 nt
	v_lshl_add_u64 v[2:3], v[62:63], 0, s[48:49]
	s_or_b32 s48, s60, 11
	s_mov_b32 s49, s61
	s_lshl_b64 s[48:49], s[48:49], 12
	v_lshl_add_u64 v[4:5], v[62:63], 0, s[48:49]
	s_or_b32 s48, s60, 12
	s_mov_b32 s49, s61
	s_lshl_b64 s[48:49], s[48:49], 12
	global_load_dwordx4 v[22:25], v[2:3], off sc1 nt
	global_load_dwordx4 v[18:21], v[4:5], off sc1 nt
	v_lshl_add_u64 v[2:3], v[62:63], 0, s[48:49]
	s_or_b32 s48, s60, 13
	s_mov_b32 s49, s61
	s_lshl_b64 s[48:49], s[48:49], 12
	v_lshl_add_u64 v[4:5], v[62:63], 0, s[48:49]
	s_or_b32 s48, s60, 14
	s_mov_b32 s49, s61
	s_lshl_b64 s[48:49], s[48:49], 12
	s_or_b32 s60, s60, 15
	global_load_dwordx4 v[14:17], v[2:3], off sc1 nt
	global_load_dwordx4 v[10:13], v[4:5], off sc1 nt
	v_lshl_add_u64 v[2:3], v[62:63], 0, s[48:49]
	s_lshl_b64 s[48:49], s[60:61], 12
	v_lshl_add_u64 v[4:5], v[62:63], 0, s[48:49]
	global_load_dwordx4 v[6:9], v[2:3], off sc1 nt
	s_nop 0
	global_load_dwordx4 v[2:5], v[4:5], off sc1 nt
	s_lshl_b32 s60, s0, 6
	s_waitcnt vmcnt(15)
	v_mul_f32_e32 v69, v69, v65
	v_mul_f32_e32 v71, v71, v67
	v_fmac_f32_e32 v69, v68, v64
	v_fmac_f32_e32 v71, v70, v66
	v_add_f32_e32 v68, v69, v71
	s_waitcnt vmcnt(14)
	v_mul_f32_e32 v59, v59, v65
	v_fmac_f32_e32 v59, v58, v64
	v_mul_f32_e32 v58, v61, v67
	v_fmac_f32_e32 v58, v60, v66
	v_add_f32_e32 v58, v59, v58
	s_waitcnt vmcnt(13)
	v_mul_f32_e32 v55, v55, v65
	v_fmac_f32_e32 v55, v54, v64
	v_mul_f32_e32 v54, v57, v67
	v_fmac_f32_e32 v54, v56, v66
	v_add_f32_e32 v54, v55, v54
	s_waitcnt vmcnt(12)
	v_mul_f32_e32 v51, v51, v65
	v_fmac_f32_e32 v51, v50, v64
	v_mul_f32_e32 v50, v53, v67
	v_fmac_f32_e32 v50, v52, v66
	v_add_f32_e32 v50, v51, v50
	s_waitcnt vmcnt(11)
	v_mul_f32_e32 v47, v47, v65
	v_fmac_f32_e32 v47, v46, v64
	v_mul_f32_e32 v46, v49, v67
	v_fmac_f32_e32 v46, v48, v66
	v_add_f32_e32 v46, v47, v46
	s_waitcnt vmcnt(10)
	v_mul_f32_e32 v43, v43, v65
	v_fmac_f32_e32 v43, v42, v64
	v_mul_f32_e32 v42, v45, v67
	v_fmac_f32_e32 v42, v44, v66
	v_add_f32_e32 v42, v43, v42
	s_waitcnt vmcnt(9)
	v_mul_f32_e32 v39, v39, v65
	v_fmac_f32_e32 v39, v38, v64
	v_mul_f32_e32 v38, v41, v67
	v_fmac_f32_e32 v38, v40, v66
	v_add_f32_e32 v38, v39, v38
	s_waitcnt vmcnt(8)
	v_mul_f32_e32 v35, v35, v65
	v_fmac_f32_e32 v35, v34, v64
	v_mul_f32_e32 v34, v37, v67
	v_fmac_f32_e32 v34, v36, v66
	v_add_f32_e32 v34, v35, v34
	s_waitcnt vmcnt(7)
	v_mul_f32_e32 v31, v31, v65
	v_fmac_f32_e32 v31, v30, v64
	v_mul_f32_e32 v30, v33, v67
	v_fmac_f32_e32 v30, v32, v66
	v_add_f32_e32 v30, v31, v30
	s_waitcnt vmcnt(6)
	v_mul_f32_e32 v27, v27, v65
	v_fmac_f32_e32 v27, v26, v64
	v_mul_f32_e32 v26, v29, v67
	v_fmac_f32_e32 v26, v28, v66
	v_add_f32_e32 v26, v27, v26
	s_waitcnt vmcnt(5)
	v_mul_f32_e32 v23, v23, v65
	v_fmac_f32_e32 v23, v22, v64
	v_mul_f32_e32 v22, v25, v67
	v_fmac_f32_e32 v22, v24, v66
	v_add_f32_e32 v22, v23, v22
	s_waitcnt vmcnt(4)
	v_mul_f32_e32 v19, v19, v65
	v_fmac_f32_e32 v19, v18, v64
	v_mul_f32_e32 v18, v21, v67
	v_fmac_f32_e32 v18, v20, v66
	v_add_f32_e32 v18, v19, v18
	s_waitcnt vmcnt(3)
	v_mul_f32_e32 v15, v15, v65
	v_fmac_f32_e32 v15, v14, v64
	v_mul_f32_e32 v14, v17, v67
	v_fmac_f32_e32 v14, v16, v66
	v_add_f32_e32 v14, v15, v14
	s_waitcnt vmcnt(2)
	v_mul_f32_e32 v11, v11, v65
	v_fmac_f32_e32 v11, v10, v64
	v_mul_f32_e32 v10, v13, v67
	v_fmac_f32_e32 v10, v12, v66
	v_add_f32_e32 v10, v11, v10
	s_waitcnt vmcnt(1)
	v_mul_f32_e32 v7, v7, v65
	v_fmac_f32_e32 v7, v6, v64
	v_mul_f32_e32 v6, v9, v67
	v_fmac_f32_e32 v6, v8, v66
	v_add_f32_e32 v6, v7, v6
	s_waitcnt vmcnt(0)
	v_mul_f32_e32 v3, v3, v65
	v_fmac_f32_e32 v3, v2, v64
	v_mul_f32_e32 v2, v5, v67
	v_fmac_f32_e32 v2, v4, v66
	v_add_f32_e32 v2, v3, v2
	ds_bpermute_b32 v69, v200, v68
	ds_bpermute_b32 v59, v200, v58
	ds_bpermute_b32 v55, v200, v54
	ds_bpermute_b32 v51, v200, v50
	ds_bpermute_b32 v47, v200, v46
	ds_bpermute_b32 v43, v200, v42
	ds_bpermute_b32 v39, v200, v38
	ds_bpermute_b32 v35, v200, v34
	s_waitcnt lgkmcnt(7)
	v_add_f32_e32 v68, v68, v69
	s_waitcnt lgkmcnt(6)
	v_add_f32_e32 v58, v58, v59
	s_waitcnt lgkmcnt(5)
	v_add_f32_e32 v54, v54, v55
	s_waitcnt lgkmcnt(4)
	v_add_f32_e32 v50, v50, v51
	s_waitcnt lgkmcnt(3)
	v_add_f32_e32 v46, v46, v47
	s_waitcnt lgkmcnt(2)
	v_add_f32_e32 v42, v42, v43
	s_waitcnt lgkmcnt(1)
	v_add_f32_e32 v38, v38, v39
	s_waitcnt lgkmcnt(0)
	v_add_f32_e32 v34, v34, v35
	ds_bpermute_b32 v69, v201, v68
	ds_bpermute_b32 v59, v201, v58
	ds_bpermute_b32 v55, v201, v54
	ds_bpermute_b32 v51, v201, v50
	ds_bpermute_b32 v47, v201, v46
	ds_bpermute_b32 v43, v201, v42
	ds_bpermute_b32 v39, v201, v38
	ds_bpermute_b32 v35, v201, v34
	s_waitcnt lgkmcnt(7)
	v_add_f32_e32 v68, v68, v69
	s_waitcnt lgkmcnt(6)
	v_add_f32_e32 v58, v58, v59
	s_waitcnt lgkmcnt(5)
	v_add_f32_e32 v54, v54, v55
	s_waitcnt lgkmcnt(4)
	v_add_f32_e32 v50, v50, v51
	s_waitcnt lgkmcnt(3)
	v_add_f32_e32 v46, v46, v47
	s_waitcnt lgkmcnt(2)
	v_add_f32_e32 v42, v42, v43
	s_waitcnt lgkmcnt(1)
	v_add_f32_e32 v38, v38, v39
	s_waitcnt lgkmcnt(0)
	v_add_f32_e32 v34, v34, v35
	ds_bpermute_b32 v69, v202, v68
	ds_bpermute_b32 v59, v202, v58
	ds_bpermute_b32 v55, v202, v54
	ds_bpermute_b32 v51, v202, v50
	ds_bpermute_b32 v47, v202, v46
	ds_bpermute_b32 v43, v202, v42
	ds_bpermute_b32 v39, v202, v38
	ds_bpermute_b32 v35, v202, v34
	s_waitcnt lgkmcnt(7)
	v_add_f32_e32 v68, v68, v69
	s_waitcnt lgkmcnt(6)
	v_add_f32_e32 v58, v58, v59
	s_waitcnt lgkmcnt(5)
	v_add_f32_e32 v54, v54, v55
	s_waitcnt lgkmcnt(4)
	v_add_f32_e32 v50, v50, v51
	s_waitcnt lgkmcnt(3)
	v_add_f32_e32 v46, v46, v47
	s_waitcnt lgkmcnt(2)
	v_add_f32_e32 v42, v42, v43
	s_waitcnt lgkmcnt(1)
	v_add_f32_e32 v38, v38, v39
	s_waitcnt lgkmcnt(0)
	v_add_f32_e32 v34, v34, v35
	ds_bpermute_b32 v69, v203, v68
	ds_bpermute_b32 v59, v203, v58
	ds_bpermute_b32 v55, v203, v54
	ds_bpermute_b32 v51, v203, v50
	ds_bpermute_b32 v47, v203, v46
	ds_bpermute_b32 v43, v203, v42
	ds_bpermute_b32 v39, v203, v38
	ds_bpermute_b32 v35, v203, v34
	s_waitcnt lgkmcnt(7)
	v_add_f32_e32 v68, v68, v69
	s_waitcnt lgkmcnt(6)
	v_add_f32_e32 v58, v58, v59
	s_waitcnt lgkmcnt(5)
	v_add_f32_e32 v54, v54, v55
	s_waitcnt lgkmcnt(4)
	v_add_f32_e32 v50, v50, v51
	s_waitcnt lgkmcnt(3)
	v_add_f32_e32 v46, v46, v47
	s_waitcnt lgkmcnt(2)
	v_add_f32_e32 v42, v42, v43
	s_waitcnt lgkmcnt(1)
	v_add_f32_e32 v38, v38, v39
	s_waitcnt lgkmcnt(0)
	v_add_f32_e32 v34, v34, v35
	ds_bpermute_b32 v69, v204, v68
	ds_bpermute_b32 v59, v204, v58
	ds_bpermute_b32 v55, v204, v54
	ds_bpermute_b32 v51, v204, v50
	ds_bpermute_b32 v47, v204, v46
	ds_bpermute_b32 v43, v204, v42
	ds_bpermute_b32 v39, v204, v38
	ds_bpermute_b32 v35, v204, v34
	s_waitcnt lgkmcnt(7)
	v_add_f32_e32 v68, v68, v69
	s_waitcnt lgkmcnt(6)
	v_add_f32_e32 v58, v58, v59
	s_waitcnt lgkmcnt(5)
	v_add_f32_e32 v54, v54, v55
	s_waitcnt lgkmcnt(4)
	v_add_f32_e32 v50, v50, v51
	s_waitcnt lgkmcnt(3)
	v_add_f32_e32 v46, v46, v47
	s_waitcnt lgkmcnt(2)
	v_add_f32_e32 v42, v42, v43
	s_waitcnt lgkmcnt(1)
	v_add_f32_e32 v38, v38, v39
	s_waitcnt lgkmcnt(0)
	v_add_f32_e32 v34, v34, v35
	ds_bpermute_b32 v69, v205, v68
	ds_bpermute_b32 v59, v205, v58
	ds_bpermute_b32 v55, v205, v54
	ds_bpermute_b32 v51, v205, v50
	ds_bpermute_b32 v47, v205, v46
	ds_bpermute_b32 v43, v205, v42
	ds_bpermute_b32 v39, v205, v38
	ds_bpermute_b32 v35, v205, v34
	s_waitcnt lgkmcnt(7)
	v_add_f32_e32 v68, v68, v69
	s_waitcnt lgkmcnt(6)
	v_add_f32_e32 v58, v58, v59
	s_waitcnt lgkmcnt(5)
	v_add_f32_e32 v54, v54, v55
	s_waitcnt lgkmcnt(4)
	v_add_f32_e32 v50, v50, v51
	s_waitcnt lgkmcnt(3)
	v_add_f32_e32 v46, v46, v47
	s_waitcnt lgkmcnt(2)
	v_add_f32_e32 v42, v42, v43
	s_waitcnt lgkmcnt(1)
	v_add_f32_e32 v38, v38, v39
	s_waitcnt lgkmcnt(0)
	v_add_f32_e32 v34, v34, v35
	ds_bpermute_b32 v31, v200, v30
	ds_bpermute_b32 v27, v200, v26
	ds_bpermute_b32 v23, v200, v22
	ds_bpermute_b32 v19, v200, v18
	ds_bpermute_b32 v15, v200, v14
	ds_bpermute_b32 v11, v200, v10
	ds_bpermute_b32 v7, v200, v6
	ds_bpermute_b32 v3, v200, v2
	s_waitcnt lgkmcnt(7)
	v_add_f32_e32 v30, v30, v31
	s_waitcnt lgkmcnt(6)
	v_add_f32_e32 v26, v26, v27
	s_waitcnt lgkmcnt(5)
	v_add_f32_e32 v22, v22, v23
	s_waitcnt lgkmcnt(4)
	v_add_f32_e32 v18, v18, v19
	s_waitcnt lgkmcnt(3)
	v_add_f32_e32 v14, v14, v15
	s_waitcnt lgkmcnt(2)
	v_add_f32_e32 v10, v10, v11
	s_waitcnt lgkmcnt(1)
	v_add_f32_e32 v6, v6, v7
	s_waitcnt lgkmcnt(0)
	v_add_f32_e32 v2, v2, v3
	ds_bpermute_b32 v31, v201, v30
	ds_bpermute_b32 v27, v201, v26
	ds_bpermute_b32 v23, v201, v22
	ds_bpermute_b32 v19, v201, v18
	ds_bpermute_b32 v15, v201, v14
	ds_bpermute_b32 v11, v201, v10
	ds_bpermute_b32 v7, v201, v6
	ds_bpermute_b32 v3, v201, v2
	s_waitcnt lgkmcnt(7)
	v_add_f32_e32 v30, v30, v31
	s_waitcnt lgkmcnt(6)
	v_add_f32_e32 v26, v26, v27
	s_waitcnt lgkmcnt(5)
	v_add_f32_e32 v22, v22, v23
	s_waitcnt lgkmcnt(4)
	v_add_f32_e32 v18, v18, v19
	s_waitcnt lgkmcnt(3)
	v_add_f32_e32 v14, v14, v15
	s_waitcnt lgkmcnt(2)
	v_add_f32_e32 v10, v10, v11
	s_waitcnt lgkmcnt(1)
	v_add_f32_e32 v6, v6, v7
	s_waitcnt lgkmcnt(0)
	v_add_f32_e32 v2, v2, v3
	ds_bpermute_b32 v31, v202, v30
	ds_bpermute_b32 v27, v202, v26
	ds_bpermute_b32 v23, v202, v22
	ds_bpermute_b32 v19, v202, v18
	ds_bpermute_b32 v15, v202, v14
	ds_bpermute_b32 v11, v202, v10
	ds_bpermute_b32 v7, v202, v6
	ds_bpermute_b32 v3, v202, v2
	s_waitcnt lgkmcnt(7)
	v_add_f32_e32 v30, v30, v31
	s_waitcnt lgkmcnt(6)
	v_add_f32_e32 v26, v26, v27
	s_waitcnt lgkmcnt(5)
	v_add_f32_e32 v22, v22, v23
	s_waitcnt lgkmcnt(4)
	v_add_f32_e32 v18, v18, v19
	s_waitcnt lgkmcnt(3)
	v_add_f32_e32 v14, v14, v15
	s_waitcnt lgkmcnt(2)
	v_add_f32_e32 v10, v10, v11
	s_waitcnt lgkmcnt(1)
	v_add_f32_e32 v6, v6, v7
	s_waitcnt lgkmcnt(0)
	v_add_f32_e32 v2, v2, v3
	ds_bpermute_b32 v31, v203, v30
	ds_bpermute_b32 v27, v203, v26
	ds_bpermute_b32 v23, v203, v22
	ds_bpermute_b32 v19, v203, v18
	ds_bpermute_b32 v15, v203, v14
	ds_bpermute_b32 v11, v203, v10
	ds_bpermute_b32 v7, v203, v6
	ds_bpermute_b32 v3, v203, v2
	s_waitcnt lgkmcnt(7)
	v_add_f32_e32 v30, v30, v31
	s_waitcnt lgkmcnt(6)
	v_add_f32_e32 v26, v26, v27
	s_waitcnt lgkmcnt(5)
	v_add_f32_e32 v22, v22, v23
	s_waitcnt lgkmcnt(4)
	v_add_f32_e32 v18, v18, v19
	s_waitcnt lgkmcnt(3)
	v_add_f32_e32 v14, v14, v15
	s_waitcnt lgkmcnt(2)
	v_add_f32_e32 v10, v10, v11
	s_waitcnt lgkmcnt(1)
	v_add_f32_e32 v6, v6, v7
	s_waitcnt lgkmcnt(0)
	v_add_f32_e32 v2, v2, v3
	ds_bpermute_b32 v31, v204, v30
	ds_bpermute_b32 v27, v204, v26
	ds_bpermute_b32 v23, v204, v22
	ds_bpermute_b32 v19, v204, v18
	ds_bpermute_b32 v15, v204, v14
	ds_bpermute_b32 v11, v204, v10
	ds_bpermute_b32 v7, v204, v6
	ds_bpermute_b32 v3, v204, v2
	s_waitcnt lgkmcnt(7)
	v_add_f32_e32 v30, v30, v31
	s_waitcnt lgkmcnt(6)
	v_add_f32_e32 v26, v26, v27
	s_waitcnt lgkmcnt(5)
	v_add_f32_e32 v22, v22, v23
	s_waitcnt lgkmcnt(4)
	v_add_f32_e32 v18, v18, v19
	s_waitcnt lgkmcnt(3)
	v_add_f32_e32 v14, v14, v15
	s_waitcnt lgkmcnt(2)
	v_add_f32_e32 v10, v10, v11
	s_waitcnt lgkmcnt(1)
	v_add_f32_e32 v6, v6, v7
	s_waitcnt lgkmcnt(0)
	v_add_f32_e32 v2, v2, v3
	ds_bpermute_b32 v31, v205, v30
	ds_bpermute_b32 v27, v205, v26
	ds_bpermute_b32 v23, v205, v22
	ds_bpermute_b32 v19, v205, v18
	ds_bpermute_b32 v15, v205, v14
	ds_bpermute_b32 v11, v205, v10
	ds_bpermute_b32 v7, v205, v6
	ds_bpermute_b32 v3, v205, v2
	s_waitcnt lgkmcnt(7)
	v_add_f32_e32 v30, v30, v31
	s_waitcnt lgkmcnt(6)
	v_add_f32_e32 v26, v26, v27
	s_waitcnt lgkmcnt(5)
	v_add_f32_e32 v22, v22, v23
	s_waitcnt lgkmcnt(4)
	v_add_f32_e32 v18, v18, v19
	s_waitcnt lgkmcnt(3)
	v_add_f32_e32 v14, v14, v15
	s_waitcnt lgkmcnt(2)
	v_add_f32_e32 v10, v10, v11
	s_waitcnt lgkmcnt(1)
	v_add_f32_e32 v6, v6, v7
	s_waitcnt lgkmcnt(0)
	v_add_f32_e32 v2, v2, v3
	s_add_i32 s0, s84, s60
	v_mov_b32_e32 v69, s0
	s_and_saveexec_b64 vcc, s[14:15]
	ds_write_b32 v69, v68
	s_or_b64 exec, exec, vcc
	s_and_saveexec_b64 vcc, s[16:17]
	ds_write_b32 v69, v58 offset:4
	s_or_b64 exec, exec, vcc
	s_and_saveexec_b64 vcc, s[18:19]
	ds_write_b32 v69, v54 offset:8
	s_or_b64 exec, exec, vcc
	s_and_saveexec_b64 vcc, s[20:21]
	ds_write_b32 v69, v50 offset:12
	s_or_b64 exec, exec, vcc
	s_and_saveexec_b64 vcc, s[22:23]
	ds_write_b32 v69, v46 offset:16
	s_or_b64 exec, exec, vcc
	s_and_saveexec_b64 vcc, s[24:25]
	ds_write_b32 v69, v42 offset:20
	s_or_b64 exec, exec, vcc
	s_and_saveexec_b64 vcc, s[26:27]
	ds_write_b32 v69, v38 offset:24
	s_or_b64 exec, exec, vcc
	s_and_saveexec_b64 vcc, s[28:29]
	ds_write_b32 v69, v34 offset:28
	s_or_b64 exec, exec, vcc
	s_and_saveexec_b64 vcc, s[30:31]
	ds_write_b32 v69, v30 offset:32
	s_or_b64 exec, exec, vcc
	s_and_saveexec_b64 vcc, s[34:35]
	ds_write_b32 v69, v26 offset:36
	s_or_b64 exec, exec, vcc
	s_and_saveexec_b64 vcc, s[36:37]
	ds_write_b32 v69, v22 offset:40
	s_or_b64 exec, exec, vcc
	s_and_saveexec_b64 vcc, s[38:39]
	ds_write_b32 v69, v18 offset:44
	s_or_b64 exec, exec, vcc
	s_and_saveexec_b64 vcc, s[40:41]
	ds_write_b32 v69, v14 offset:48
	s_or_b64 exec, exec, vcc
	s_and_saveexec_b64 vcc, s[42:43]
	ds_write_b32 v69, v10 offset:52
	s_or_b64 exec, exec, vcc
	s_and_saveexec_b64 vcc, s[44:45]
	ds_write_b32 v69, v6 offset:56
	s_or_b64 exec, exec, vcc
	s_and_saveexec_b64 vcc, s[46:47]
	ds_write_b32 v69, v2 offset:60
	s_branch .LBB11_2192
.LBB11_2225:
	s_add_u32 s0, s58, s90
	s_addc_u32 s1, s59, s91
	s_lshl_b32 s10, s68, 2
	s_add_u32 s0, s0, s10
	s_addc_u32 s1, s1, 0
	v_lshl_add_u64 v[66:67], v[100:101], 2, s[0:1]
	v_readlane_b32 s0, v243, 2
	v_readlane_b32 s1, v243, 3
	v_mov_b32_e32 v105, s84
	s_waitcnt lgkmcnt(0)
	v_lshl_add_u64 v[2:3], v[66:67], 0, s[0:1]
	v_readlane_b32 s0, v244, 4
	v_readlane_b32 s1, v244, 5
	s_nop 1
	v_lshl_add_u64 v[4:5], v[66:67], 0, s[0:1]
	v_readlane_b32 s0, v244, 6
	v_readlane_b32 s1, v244, 7
	global_load_dwordx4 v[62:65], v[2:3], off sc1 nt
	global_load_dwordx4 v[42:45], v[4:5], off sc1 nt
	v_lshl_add_u64 v[2:3], v[66:67], 0, s[0:1]
	v_readlane_b32 s0, v244, 8
	v_readlane_b32 s1, v244, 9
	s_nop 1
	v_lshl_add_u64 v[4:5], v[66:67], 0, s[0:1]
	v_readlane_b32 s0, v244, 10
	v_readlane_b32 s1, v244, 11
	global_load_dwordx4 v[58:61], v[2:3], off sc1 nt
	global_load_dwordx4 v[34:37], v[4:5], off sc1 nt
	v_lshl_add_u64 v[2:3], v[66:67], 0, s[0:1]
	v_readlane_b32 s0, v244, 12
	v_readlane_b32 s1, v244, 13
	s_nop 1
	v_lshl_add_u64 v[4:5], v[66:67], 0, s[0:1]
	v_readlane_b32 s0, v244, 14
	v_readlane_b32 s1, v244, 15
	global_load_dwordx4 v[54:57], v[2:3], off sc1 nt
	global_load_dwordx4 v[26:29], v[4:5], off sc1 nt
	v_lshl_add_u64 v[2:3], v[66:67], 0, s[0:1]
	v_readlane_b32 s0, v244, 16
	v_readlane_b32 s1, v244, 17
	s_nop 1
	v_lshl_add_u64 v[4:5], v[66:67], 0, s[0:1]
	v_readlane_b32 s0, v244, 18
	v_readlane_b32 s1, v244, 19
	global_load_dwordx4 v[50:53], v[2:3], off sc1 nt
	global_load_dwordx4 v[22:25], v[4:5], off sc1 nt
	v_lshl_add_u64 v[2:3], v[66:67], 0, s[0:1]
	v_readlane_b32 s0, v244, 20
	v_readlane_b32 s1, v244, 21
	s_nop 1
	v_lshl_add_u64 v[4:5], v[66:67], 0, s[0:1]
	v_readlane_b32 s0, v244, 22
	v_readlane_b32 s1, v244, 23
	global_load_dwordx4 v[46:49], v[2:3], off sc1 nt
	global_load_dwordx4 v[18:21], v[4:5], off sc1 nt
	v_lshl_add_u64 v[2:3], v[66:67], 0, s[0:1]
	v_readlane_b32 s0, v244, 24
	v_readlane_b32 s1, v244, 25
	s_nop 1
	v_lshl_add_u64 v[4:5], v[66:67], 0, s[0:1]
	v_readlane_b32 s0, v244, 26
	v_readlane_b32 s1, v244, 27
	global_load_dwordx4 v[38:41], v[2:3], off sc1 nt
	global_load_dwordx4 v[14:17], v[4:5], off sc1 nt
	v_lshl_add_u64 v[2:3], v[66:67], 0, s[0:1]
	v_readlane_b32 s0, v244, 28
	v_readlane_b32 s1, v244, 29
	s_nop 1
	v_lshl_add_u64 v[4:5], v[66:67], 0, s[0:1]
	v_readlane_b32 s0, v244, 30
	v_readlane_b32 s1, v244, 31
	global_load_dwordx4 v[30:33], v[2:3], off sc1 nt
	global_load_dwordx4 v[10:13], v[4:5], off sc1 nt
	v_lshl_add_u64 v[2:3], v[66:67], 0, s[0:1]
	v_readlane_b32 s0, v244, 32
	v_readlane_b32 s1, v244, 33
	s_nop 1
	v_lshl_add_u64 v[4:5], v[66:67], 0, s[0:1]
	global_load_dwordx4 v[6:9], v[2:3], off sc1 nt
	s_nop 0
	global_load_dwordx4 v[2:5], v[4:5], off sc1 nt
	s_waitcnt lgkmcnt(0)
	s_barrier
	ds_read2st64_b32 v[68:69], v0 offset1:1
	ds_read2st64_b32 v[70:71], v0 offset0:2 offset1:3
	s_waitcnt lgkmcnt(1)
	v_max3_f32 v72, v68, s72, v69
	s_waitcnt lgkmcnt(0)
	v_max3_f32 v72, v72, v70, v71
	ds_bpermute_b32 v73, v200, v72
	s_waitcnt lgkmcnt(0)
	v_max_f32_e32 v73, v73, v73
	v_max_f32_e32 v72, v72, v73
	ds_bpermute_b32 v73, v201, v72
	s_waitcnt lgkmcnt(0)
	v_max_f32_e32 v73, v73, v73
	v_max_f32_e32 v72, v72, v73
	ds_bpermute_b32 v73, v202, v72
	s_waitcnt lgkmcnt(0)
	v_max_f32_e32 v73, v73, v73
	v_max_f32_e32 v72, v72, v73
	ds_bpermute_b32 v73, v203, v72
	s_waitcnt lgkmcnt(0)
	v_max_f32_e32 v73, v73, v73
	v_max_f32_e32 v72, v72, v73
	ds_bpermute_b32 v73, v204, v72
	s_waitcnt lgkmcnt(0)
	v_max_f32_e32 v73, v73, v73
	v_max_f32_e32 v72, v72, v73
	ds_bpermute_b32 v73, v205, v72
	s_waitcnt lgkmcnt(0)
	v_max_f32_e32 v73, v73, v73
	v_max_f32_e32 v104, v72, v73
	v_sub_f32_e32 v68, v68, v104
	v_mul_f32_e32 v68, 0x3fb8aa3b, v68
	v_sub_f32_e32 v69, v69, v104
	v_exp_f32_e32 v68, v68
	v_mul_f32_e32 v69, 0x3fb8aa3b, v69
	v_sub_f32_e32 v70, v70, v104
	v_exp_f32_e32 v69, v69
	v_mul_f32_e32 v70, 0x3fb8aa3b, v70
	v_sub_f32_e32 v71, v71, v104
	v_exp_f32_e32 v70, v70
	v_mul_f32_e32 v71, 0x3fb8aa3b, v71
	v_exp_f32_e32 v71, v71
	v_add_f32_e32 v68, 0, v68
	v_add_f32_e32 v68, v69, v68
	v_add_f32_e32 v68, v70, v68
	v_add_f32_e32 v68, v71, v68
	ds_bpermute_b32 v69, v200, v68
	s_waitcnt lgkmcnt(0)
	v_add_f32_e32 v68, v68, v69
	ds_bpermute_b32 v69, v201, v68
	s_waitcnt lgkmcnt(0)
	v_add_f32_e32 v68, v68, v69
	ds_bpermute_b32 v69, v202, v68
	s_waitcnt lgkmcnt(0)
	v_add_f32_e32 v68, v68, v69
	ds_bpermute_b32 v69, v203, v68
	s_waitcnt lgkmcnt(0)
	v_add_f32_e32 v76, v68, v69
	ds_bpermute_b32 v77, v204, v76
	ds_read_b128 v[68:71], v105
	ds_read_b128 v[72:75], v105 offset:16
	s_waitcnt lgkmcnt(2)
	v_add_f32_e32 v84, v76, v77
	ds_bpermute_b32 v85, v205, v84
	s_waitcnt lgkmcnt(2)
	v_sub_f32_e32 v68, v68, v104
	v_mul_f32_e32 v68, 0x3fb8aa3b, v68
	v_exp_f32_e32 v68, v68
	ds_read_b128 v[76:79], v105 offset:32
	ds_read_b128 v[80:83], v105 offset:48
	s_waitcnt lgkmcnt(2)
	v_add_f32_e32 v84, v84, v85
	v_div_scale_f32 v85, s[0:1], v84, v84, 1.0
	v_rcp_f32_e32 v86, v85
	v_div_scale_f32 v87, vcc, 1.0, v84, 1.0
	v_readlane_b32 s0, v244, 34
	v_fma_f32 v88, -v85, v86, 1.0
	v_fmac_f32_e32 v86, v88, v86
	v_mul_f32_e32 v88, v87, v86
	v_fma_f32 v89, -v85, v88, v87
	v_fmac_f32_e32 v88, v89, v86
	v_fma_f32 v85, -v85, v88, v87
	v_div_fmas_f32 v85, v85, v86, v88
	v_div_fixup_f32 v139, v85, v84, 1.0
	v_mul_f32_e32 v138, v68, v139
	v_sub_f32_e32 v68, v69, v104
	v_sub_f32_e32 v69, v70, v104
	v_mul_f32_e32 v68, 0x3fb8aa3b, v68
	v_mul_f32_e32 v69, 0x3fb8aa3b, v69
	v_sub_f32_e32 v70, v71, v104
	v_exp_f32_e32 v68, v68
	v_exp_f32_e32 v69, v69
	v_mul_f32_e32 v70, 0x3fb8aa3b, v70
	v_exp_f32_e32 v70, v70
	v_sub_f32_e32 v71, v72, v104
	v_mul_f32_e32 v71, 0x3fb8aa3b, v71
	v_mul_f32_e32 v140, v68, v139
	v_mul_f32_e32 v142, v69, v139
	v_sub_f32_e32 v68, v73, v104
	v_sub_f32_e32 v69, v74, v104
	v_exp_f32_e32 v71, v71
	v_mul_f32_e32 v144, v70, v139
	v_mul_f32_e32 v68, 0x3fb8aa3b, v68
	v_mul_f32_e32 v69, 0x3fb8aa3b, v69
	v_sub_f32_e32 v70, v75, v104
	v_exp_f32_e32 v68, v68
	v_exp_f32_e32 v69, v69
	v_mul_f32_e32 v70, 0x3fb8aa3b, v70
	v_exp_f32_e32 v70, v70
	v_mul_f32_e32 v146, v71, v139
	s_waitcnt lgkmcnt(1)
	v_sub_f32_e32 v71, v76, v104
	v_mul_f32_e32 v71, 0x3fb8aa3b, v71
	v_mul_f32_e32 v148, v68, v139
	v_mul_f32_e32 v150, v139, v69
	v_sub_f32_e32 v68, v77, v104
	v_sub_f32_e32 v69, v78, v104
	v_exp_f32_e32 v71, v71
	v_mul_f32_e32 v152, v139, v70
	v_mul_f32_e32 v68, 0x3fb8aa3b, v68
	v_mul_f32_e32 v69, 0x3fb8aa3b, v69
	v_sub_f32_e32 v70, v79, v104
	v_exp_f32_e32 v68, v68
	v_exp_f32_e32 v69, v69
	v_mul_f32_e32 v70, 0x3fb8aa3b, v70
	v_exp_f32_e32 v70, v70
	v_mul_f32_e32 v154, v139, v71
	s_waitcnt lgkmcnt(0)
	v_sub_f32_e32 v71, v80, v104
	v_readlane_b32 s1, v244, 35
	v_mul_f32_e32 v71, 0x3fb8aa3b, v71
	v_mul_f32_e32 v156, v139, v68
	v_mul_f32_e32 v158, v139, v69
	v_lshl_add_u64 v[68:69], v[66:67], 0, s[0:1]
	v_exp_f32_e32 v71, v71
	v_mul_f32_e32 v160, v139, v70
	v_sub_f32_e32 v70, v81, v104
	global_load_dwordx4 v[106:109], v[68:69], off sc1 nt
	v_mul_f32_e32 v68, 0x3fb8aa3b, v70
	v_exp_f32_e32 v70, v68
	v_sub_f32_e32 v68, v82, v104
	v_mul_f32_e32 v68, 0x3fb8aa3b, v68
	v_readlane_b32 s0, v244, 36
	v_mul_f32_e32 v162, v139, v71
	v_exp_f32_e32 v71, v68
	v_sub_f32_e32 v68, v83, v104
	v_readlane_b32 s1, v244, 37
	v_mul_f32_e32 v72, 0x3fb8aa3b, v68
	v_mul_f32_e32 v164, v139, v70
	v_lshl_add_u64 v[68:69], v[66:67], 0, s[0:1]
	v_readlane_b32 s0, v244, 38
	v_readlane_b32 s1, v244, 39
	global_load_dwordx4 v[110:113], v[68:69], off sc1 nt
	v_mul_f32_e32 v166, v139, v71
	v_lshl_add_u64 v[68:69], v[66:67], 0, s[0:1]
	global_load_dwordx4 v[114:117], v[68:69], off sc1 nt
	v_readlane_b32 s0, v244, 40
	v_readlane_b32 s1, v244, 41
	v_exp_f32_e32 v72, v72
	s_waitcnt vmcnt(18)
	v_pk_fma_f32 v[62:63], v[62:63], v[138:139], 0 op_sel_hi:[1,0,0]
	v_lshl_add_u64 v[68:69], v[66:67], 0, s[0:1]
	v_readlane_b32 s0, v244, 42
	v_readlane_b32 s1, v244, 43
	global_load_dwordx4 v[118:121], v[68:69], off sc1 nt
	v_mul_f32_e32 v168, v139, v72
	v_lshl_add_u64 v[68:69], v[66:67], 0, s[0:1]
	v_readlane_b32 s0, v244, 44
	v_readlane_b32 s1, v244, 45
	v_pk_fma_f32 v[64:65], v[64:65], v[138:139], 0 op_sel_hi:[1,0,0]
	s_waitcnt vmcnt(18)
	v_pk_fma_f32 v[42:43], v[42:43], v[140:141], v[62:63] op_sel_hi:[1,0,1]
	v_lshl_add_u64 v[70:71], v[66:67], 0, s[0:1]
	global_load_dwordx4 v[122:125], v[68:69], off sc1 nt
	global_load_dwordx4 v[126:129], v[70:71], off sc1 nt
	v_readlane_b32 s0, v244, 46
	v_readlane_b32 s1, v244, 47
	v_pk_fma_f32 v[44:45], v[44:45], v[140:141], v[64:65] op_sel_hi:[1,0,1]
	s_waitcnt vmcnt(19)
	v_pk_fma_f32 v[42:43], v[58:59], v[142:143], v[42:43] op_sel_hi:[1,0,1]
	v_lshl_add_u64 v[68:69], v[66:67], 0, s[0:1]
	v_readlane_b32 s0, v244, 48
	v_readlane_b32 s1, v244, 49
	v_pk_fma_f32 v[44:45], v[60:61], v[142:143], v[44:45] op_sel_hi:[1,0,1]
	s_waitcnt vmcnt(18)
	v_pk_fma_f32 v[34:35], v[34:35], v[144:145], v[42:43] op_sel_hi:[1,0,1]
	v_lshl_add_u64 v[70:71], v[66:67], 0, s[0:1]
	global_load_dwordx4 v[130:133], v[68:69], off sc1 nt
	global_load_dwordx4 v[134:137], v[70:71], off sc1 nt
	v_readlane_b32 s0, v244, 50
	v_readlane_b32 s1, v244, 51
	v_pk_fma_f32 v[36:37], v[36:37], v[144:145], v[44:45] op_sel_hi:[1,0,1]
	s_waitcnt vmcnt(19)
	v_pk_fma_f32 v[34:35], v[54:55], v[146:147], v[34:35] op_sel_hi:[1,0,1]
	v_lshl_add_u64 v[68:69], v[66:67], 0, s[0:1]
	v_readlane_b32 s0, v244, 52
	v_readlane_b32 s1, v244, 53
	v_pk_fma_f32 v[36:37], v[56:57], v[146:147], v[36:37] op_sel_hi:[1,0,1]
	s_waitcnt vmcnt(18)
	v_pk_fma_f32 v[26:27], v[26:27], v[148:149], v[34:35] op_sel_hi:[1,0,1]
	v_lshl_add_u64 v[70:71], v[66:67], 0, s[0:1]
	v_readlane_b32 s0, v244, 54
	v_readlane_b32 s1, v244, 55
	global_load_dwordx4 v[94:97], v[68:69], off sc1 nt
	global_load_dwordx4 v[90:93], v[70:71], off sc1 nt
	v_lshl_add_u64 v[68:69], v[66:67], 0, s[0:1]
	v_readlane_b32 s0, v244, 56
	v_readlane_b32 s1, v244, 57
	v_pk_fma_f32 v[28:29], v[28:29], v[148:149], v[36:37] op_sel_hi:[1,0,1]
	s_waitcnt vmcnt(19)
	v_pk_fma_f32 v[26:27], v[50:51], v[150:151], v[26:27] op_sel_hi:[1,0,1]
	v_lshl_add_u64 v[70:71], v[66:67], 0, s[0:1]
	v_readlane_b32 s0, v244, 58
	v_readlane_b32 s1, v244, 59
	global_load_dwordx4 v[86:89], v[68:69], off sc1 nt
	global_load_dwordx4 v[82:85], v[70:71], off sc1 nt
	v_lshl_add_u64 v[68:69], v[66:67], 0, s[0:1]
	v_readlane_b32 s0, v244, 60
	v_readlane_b32 s1, v244, 61
	v_pk_fma_f32 v[28:29], v[52:53], v[150:151], v[28:29] op_sel_hi:[1,0,1]
	s_waitcnt vmcnt(20)
	v_pk_fma_f32 v[22:23], v[22:23], v[152:153], v[26:27] op_sel_hi:[1,0,1]
	v_lshl_add_u64 v[70:71], v[66:67], 0, s[0:1]
	global_load_dwordx4 v[78:81], v[68:69], off sc1 nt
	global_load_dwordx4 v[74:77], v[70:71], off sc1 nt
	v_readlane_b32 s0, v244, 62
	v_readlane_b32 s1, v244, 63
	v_pk_fma_f32 v[24:25], v[24:25], v[152:153], v[28:29] op_sel_hi:[1,0,1]
	s_waitcnt vmcnt(21)
	v_pk_fma_f32 v[22:23], v[46:47], v[154:155], v[22:23] op_sel_hi:[1,0,1]
	v_lshl_add_u64 v[68:69], v[66:67], 0, s[0:1]
	v_readlane_b32 s0, v243, 4
	v_readlane_b32 s1, v243, 5
	v_pk_fma_f32 v[24:25], v[48:49], v[154:155], v[24:25] op_sel_hi:[1,0,1]
	s_waitcnt vmcnt(20)
	v_pk_fma_f32 v[18:19], v[18:19], v[156:157], v[22:23] op_sel_hi:[1,0,1]
	v_lshl_add_u64 v[66:67], v[66:67], 0, s[0:1]
	global_load_dwordx4 v[70:73], v[68:69], off sc1 nt
	s_nop 0
	global_load_dwordx4 v[66:69], v[66:67], off sc1 nt
	v_pk_fma_f32 v[20:21], v[20:21], v[156:157], v[24:25] op_sel_hi:[1,0,1]
	s_waitcnt vmcnt(21)
	v_pk_fma_f32 v[18:19], v[38:39], v[158:159], v[18:19] op_sel_hi:[1,0,1]
	v_pk_fma_f32 v[20:21], v[40:41], v[158:159], v[20:21] op_sel_hi:[1,0,1]
	s_waitcnt vmcnt(20)
	v_pk_fma_f32 v[14:15], v[14:15], v[160:161], v[18:19] op_sel_hi:[1,0,1]
	v_pk_fma_f32 v[16:17], v[16:17], v[160:161], v[20:21] op_sel_hi:[1,0,1]
	s_waitcnt vmcnt(19)
	v_pk_fma_f32 v[18:19], v[30:31], v[162:163], v[14:15] op_sel_hi:[1,0,1]
	v_pk_fma_f32 v[20:21], v[32:33], v[162:163], v[16:17] op_sel_hi:[1,0,1]
	ds_read_b128 v[14:17], v105 offset:64
	s_waitcnt vmcnt(18)
	v_pk_fma_f32 v[10:11], v[10:11], v[164:165], v[18:19] op_sel_hi:[1,0,1]
	v_pk_fma_f32 v[20:21], v[12:13], v[164:165], v[20:21] op_sel_hi:[1,0,1]
	s_waitcnt vmcnt(17)
	v_pk_fma_f32 v[6:7], v[6:7], v[166:167], v[10:11] op_sel_hi:[1,0,1]
	ds_read_b128 v[10:13], v105 offset:80
	s_waitcnt lgkmcnt(1)
	v_sub_f32_e32 v14, v14, v104
	v_mul_f32_e32 v14, 0x3fb8aa3b, v14
	v_exp_f32_e32 v14, v14
	v_pk_fma_f32 v[8:9], v[8:9], v[166:167], v[20:21] op_sel_hi:[1,0,1]
	s_waitcnt vmcnt(16)
	v_pk_fma_f32 v[2:3], v[2:3], v[168:169], v[6:7] op_sel_hi:[1,0,1]
	v_pk_fma_f32 v[4:5], v[4:5], v[168:169], v[8:9] op_sel_hi:[1,0,1]
	v_mul_f32_e32 v6, v139, v14
	s_waitcnt vmcnt(15)
	v_pk_fma_f32 v[2:3], v[106:107], v[6:7], v[2:3] op_sel_hi:[1,0,1]
	v_pk_fma_f32 v[4:5], v[108:109], v[6:7], v[4:5] op_sel_hi:[1,0,1]
	v_sub_f32_e32 v6, v15, v104
	v_mul_f32_e32 v6, 0x3fb8aa3b, v6
	v_sub_f32_e32 v7, v16, v104
	v_exp_f32_e32 v6, v6
	v_mul_f32_e32 v7, 0x3fb8aa3b, v7
	v_exp_f32_e32 v7, v7
	v_mul_f32_e32 v6, v139, v6
	s_waitcnt vmcnt(14)
	v_pk_fma_f32 v[4:5], v[112:113], v[6:7], v[4:5] op_sel_hi:[1,0,1]
	v_pk_fma_f32 v[2:3], v[110:111], v[6:7], v[2:3] op_sel_hi:[1,0,1]
	v_mul_f32_e32 v6, v139, v7
	s_waitcnt vmcnt(13)
	v_pk_fma_f32 v[2:3], v[114:115], v[6:7], v[2:3] op_sel_hi:[1,0,1]
	v_pk_fma_f32 v[4:5], v[116:117], v[6:7], v[4:5] op_sel_hi:[1,0,1]
	v_sub_f32_e32 v6, v17, v104
	v_mul_f32_e32 v6, 0x3fb8aa3b, v6
	s_waitcnt lgkmcnt(0)
	v_sub_f32_e32 v7, v10, v104
	v_exp_f32_e32 v6, v6
	v_mul_f32_e32 v7, 0x3fb8aa3b, v7
	v_exp_f32_e32 v7, v7
	v_mul_f32_e32 v6, v139, v6
	s_waitcnt vmcnt(12)
	v_pk_fma_f32 v[4:5], v[120:121], v[6:7], v[4:5] op_sel_hi:[1,0,1]
	v_pk_fma_f32 v[2:3], v[118:119], v[6:7], v[2:3] op_sel_hi:[1,0,1]
	v_mul_f32_e32 v6, v139, v7
	s_waitcnt vmcnt(11)
	v_pk_fma_f32 v[2:3], v[122:123], v[6:7], v[2:3] op_sel_hi:[1,0,1]
	v_pk_fma_f32 v[4:5], v[124:125], v[6:7], v[4:5] op_sel_hi:[1,0,1]
	v_sub_f32_e32 v6, v11, v104
	v_mul_f32_e32 v6, 0x3fb8aa3b, v6
	v_sub_f32_e32 v7, v12, v104
	v_exp_f32_e32 v6, v6
	v_mul_f32_e32 v7, 0x3fb8aa3b, v7
	v_exp_f32_e32 v7, v7
	v_mul_f32_e32 v6, v139, v6
	s_waitcnt vmcnt(10)
	v_pk_fma_f32 v[4:5], v[128:129], v[6:7], v[4:5] op_sel_hi:[1,0,1]
	v_pk_fma_f32 v[2:3], v[126:127], v[6:7], v[2:3] op_sel_hi:[1,0,1]
	v_mul_f32_e32 v6, v139, v7
	v_sub_f32_e32 v7, v13, v104
	v_mul_f32_e32 v7, 0x3fb8aa3b, v7
	v_exp_f32_e32 v10, v7
	s_waitcnt vmcnt(9)
	v_pk_fma_f32 v[8:9], v[130:131], v[6:7], v[2:3] op_sel_hi:[1,0,1]
	v_pk_fma_f32 v[6:7], v[132:133], v[6:7], v[4:5] op_sel_hi:[1,0,1]
	ds_read_b128 v[2:5], v105 offset:96
	v_mul_f32_e32 v10, v139, v10
	s_waitcnt vmcnt(8)
	v_pk_fma_f32 v[12:13], v[136:137], v[10:11], v[6:7] op_sel_hi:[1,0,1]
	v_pk_fma_f32 v[10:11], v[134:135], v[10:11], v[8:9] op_sel_hi:[1,0,1]
	ds_read_b128 v[6:9], v105 offset:112
	s_waitcnt lgkmcnt(1)
	v_sub_f32_e32 v2, v2, v104
	v_mul_f32_e32 v2, 0x3fb8aa3b, v2
	v_sub_f32_e32 v3, v3, v104
	v_exp_f32_e32 v2, v2
	v_mul_f32_e32 v3, 0x3fb8aa3b, v3
	v_sub_f32_e32 v4, v4, v104
	v_exp_f32_e32 v14, v3
	v_mul_f32_e32 v4, 0x3fb8aa3b, v4
	v_sub_f32_e32 v5, v5, v104
	v_exp_f32_e32 v4, v4
	v_mul_f32_e32 v5, 0x3fb8aa3b, v5
	s_waitcnt lgkmcnt(0)
	v_sub_f32_e32 v6, v6, v104
	v_exp_f32_e32 v5, v5
	v_mul_f32_e32 v6, 0x3fb8aa3b, v6
	v_sub_f32_e32 v7, v7, v104
	v_mul_f32_e32 v2, v139, v2
	v_exp_f32_e32 v6, v6
	v_mul_f32_e32 v7, 0x3fb8aa3b, v7
	s_waitcnt vmcnt(7)
	v_pk_fma_f32 v[10:11], v[94:95], v[2:3], v[10:11] op_sel_hi:[1,0,1]
	v_pk_fma_f32 v[2:3], v[96:97], v[2:3], v[12:13] op_sel_hi:[1,0,1]
	v_mul_f32_e32 v12, v139, v14
	v_exp_f32_e32 v7, v7
	s_waitcnt vmcnt(6)
	v_pk_fma_f32 v[2:3], v[92:93], v[12:13], v[2:3] op_sel_hi:[1,0,1]
	v_pk_fma_f32 v[10:11], v[90:91], v[12:13], v[10:11] op_sel_hi:[1,0,1]
	v_mul_f32_e32 v4, v139, v4
	s_waitcnt vmcnt(5)
	v_pk_fma_f32 v[10:11], v[86:87], v[4:5], v[10:11] op_sel_hi:[1,0,1]
	v_pk_fma_f32 v[2:3], v[88:89], v[4:5], v[2:3] op_sel_hi:[1,0,1]
	v_mul_f32_e32 v4, v139, v5
	s_waitcnt vmcnt(4)
	v_pk_fma_f32 v[2:3], v[84:85], v[4:5], v[2:3] op_sel_hi:[1,0,1]
	v_pk_fma_f32 v[4:5], v[82:83], v[4:5], v[10:11] op_sel_hi:[1,0,1]
	v_mul_f32_e32 v6, v139, v6
	s_waitcnt vmcnt(3)
	v_pk_fma_f32 v[4:5], v[78:79], v[6:7], v[4:5] op_sel_hi:[1,0,1]
	v_pk_fma_f32 v[2:3], v[80:81], v[6:7], v[2:3] op_sel_hi:[1,0,1]
	v_mul_f32_e32 v6, v139, v7
	s_waitcnt vmcnt(2)
	v_pk_fma_f32 v[2:3], v[76:77], v[6:7], v[2:3] op_sel_hi:[1,0,1]
	v_pk_fma_f32 v[4:5], v[74:75], v[6:7], v[4:5] op_sel_hi:[1,0,1]
	v_sub_f32_e32 v6, v8, v104
	v_mul_f32_e32 v6, 0x3fb8aa3b, v6
	v_sub_f32_e32 v7, v9, v104
	v_exp_f32_e32 v6, v6
	v_mul_f32_e32 v7, 0x3fb8aa3b, v7
	v_exp_f32_e32 v7, v7
	v_mul_f32_e32 v6, v139, v6
	s_waitcnt vmcnt(1)
	v_pk_fma_f32 v[8:9], v[70:71], v[6:7], v[4:5] op_sel_hi:[1,0,1]
	v_pk_fma_f32 v[2:3], v[72:73], v[6:7], v[2:3] op_sel_hi:[1,0,1]
	v_mul_f32_e32 v6, v139, v7
	s_waitcnt vmcnt(0)
	v_pk_fma_f32 v[4:5], v[68:69], v[6:7], v[2:3] op_sel_hi:[1,0,1]
	v_pk_fma_f32 v[2:3], v[66:67], v[6:7], v[8:9] op_sel_hi:[1,0,1]
	ds_write_b128 v102, v[2:5] offset:4096
	s_waitcnt lgkmcnt(0)
	s_waitcnt lgkmcnt(0)
	s_barrier
	s_and_saveexec_b64 s[10:11], s[12:13]
	s_cbranch_execz .LBB11_2190
	ds_read2st64_b32 v[2:3], v103 offset0:16 offset1:20
	s_lshl_b64 s[0:1], s[88:89], 1
	s_add_u32 s0, s8, s0
	s_addc_u32 s1, s9, s1
	s_lshl_b32 s48, s68, 1
	s_waitcnt lgkmcnt(0)
	v_add_f32_e32 v2, 0, v2
	v_add_f32_e32 v4, v2, v3
	ds_read2st64_b32 v[2:3], v103 offset0:24 offset1:28
	s_add_u32 s0, s0, s48
	s_addc_u32 s1, s1, 0
	s_waitcnt lgkmcnt(0)
	v_add_f32_e32 v2, v4, v2
	v_add_f32_e32 v4, v2, v3
	ds_read2st64_b32 v[2:3], v103 offset0:32 offset1:36
	s_waitcnt lgkmcnt(0)
	v_add_f32_e32 v2, v4, v2
	v_add_f32_e32 v4, v2, v3
	ds_read2st64_b32 v[2:3], v103 offset0:40 offset1:44
	s_waitcnt lgkmcnt(0)
	v_add_f32_e32 v2, v4, v2
	v_add_f32_e32 v2, v2, v3
	v_cvt_pk_bf16_f32 v4, v2, v1
	v_lshl_add_u64 v[2:3], v[98:99], 1, s[0:1]
	global_store_short v[2:3], v4, off sc1
	s_branch .LBB11_2190
